# merge tile order variant: co-resident blocks (j, j+32) share the A tile instead of the B tile
# baseline (speedup 1.0000x reference)
; __device__ __forceinline__ void phase_merge(const bf16_t* G, const bf16_t* BO, const bf16_t* Wb, bf16_t* M, bf16_t* sm) {
;     ...
;     for (int t = blockIdx.x; t < 136 * 16; t += gridDim.x) {
;         const int tm = t >> 4, tn = t & 15;
;         const int cbase = tn * 64 + wc * 32 + fq * 8;
;         f32x4 accm[4][2]; zero_acc<2>(accm);
; #pragma unroll 1
;         for (int i = 0; i < 4; ++i) {
;             f32x4 accb[4][2]; zero_acc<2>(accb);
;             const int koff = i * 512, kk = i < 3 ? 512 : 256;
;             gemm_tile<2>(accb, BO + (size_t)tm * 128 * 1792 + koff, 1792, Wb + (size_t)tn * 64 * 1792 + koff, 1792, kk, sm);
.LBB0_474:
	s_bfe_u32 s2, s42, 0x30006
	s_and_b32 s24, s42, 1
	s_lshl_b32 s24, s24, 3
	s_or_b32 s2, s2, s24
	s_and_b32 s24, s42, 15
	s_cmpk_lt_i32 s42, 0x800
	s_cselect_b32 s2, s2, s24
	s_mov_b32 s40, s2
	s_mul_i32 s2, s2, 0x38000
	s_add_u32 s22, s58, s2
	s_addc_u32 s23, s59, 0
	s_lshr_b32 s2, s43, 9
	s_lshl_b32 s2, s2, 5
	s_bfe_u32 s24, s43, 0x20001
	s_lshl_b32 s24, s24, 3
	s_or_b32 s2, s2, s24
	s_bfe_u32 s24, s43, 0x30003
	s_or_b32 s2, s2, s24
	s_ashr_i32 s24, s43, 4
	s_cmpk_lt_i32 s43, 0x800
	s_cselect_b32 s2, s2, s24
	s_mov_b32 s24, s40
	s_mul_i32 s40, s2, 0x70000
	s_mul_hi_i32 s25, s2, 0x70000
	s_add_u32 s44, s11, s40
	v_lshl_or_b32 v66, s24, 6, v67
	s_addc_u32 s45, s12, s25
	s_mul_i32 s24, s24, 0x38000
	s_add_u32 s46, s13, s24
	v_lshl_add_u32 v64, s2, 7, v114
	s_addc_u32 s47, s39, 0
	v_or_b32_e32 v62, 16, v64
	v_or_b32_e32 v60, 32, v64
	v_or_b32_e32 v58, 48, v64
	v_lshlrev_b32_e32 v12, 1, v66
	v_ashrrev_i32_e32 v65, 31, v64
	v_ashrrev_i32_e32 v63, 31, v62
	v_ashrrev_i32_e32 v61, 31, v60
	v_ashrrev_i32_e32 v59, 31, v58
	s_add_u32 s24, s58, s40
	v_mov_b32_e32 v115, 0
	v_lshl_add_u64 v[76:77], s[14:15], 0, v[12:13]
	v_lshlrev_b64 v[78:79], 13, v[64:65]
	v_lshlrev_b64 v[80:81], 13, v[62:63]
	v_lshlrev_b64 v[90:91], 13, v[60:61]
	v_lshlrev_b64 v[92:93], 13, v[58:59]
	s_addc_u32 s25, s59, s25
	s_mov_b32 s48, 0
	v_mov_b32_e32 v75, 0
	v_mov_b32_e32 v73, 0
	v_mov_b32_e32 v71, 0
	v_mov_b32_e32 v69, 0
	v_mov_b32_e32 v74, v115
	v_mov_b32_e32 v72, v115
	v_mov_b32_e32 v70, v115
	v_mov_b32_e32 v68, v115
	v_mov_b32_e32 v89, 0
	v_mov_b32_e32 v87, 0
	v_mov_b32_e32 v85, 0
	v_mov_b32_e32 v83, 0
	v_mov_b32_e32 v88, v115
	v_mov_b32_e32 v86, v115
	v_mov_b32_e32 v84, v115
	v_mov_b32_e32 v82, v115
	v_mov_b32_e32 v101, 0
	v_mov_b32_e32 v99, 0
	v_mov_b32_e32 v97, 0
	v_mov_b32_e32 v95, 0
	v_mov_b32_e32 v100, v115
	v_mov_b32_e32 v98, v115
	v_mov_b32_e32 v96, v115
	v_mov_b32_e32 v94, v115
	v_mov_b32_e32 v109, 0
	v_mov_b32_e32 v107, 0
	v_mov_b32_e32 v105, 0
	v_mov_b32_e32 v103, 0
	v_mov_b32_e32 v108, v115
	v_mov_b32_e32 v106, v115
	v_mov_b32_e32 v104, v115
	v_mov_b32_e32 v102, v115
